# MLA stagger with mid-stage barrier moved after region Y (before exp of half 1)
# speedup vs baseline: 1.0092x; 1.0032x over previous
.LBB0_520:
	v_readlane_b32 s13, v248, 13
	s_sub_i32 s4, s74, s13
	s_lshl_b32 s4, s4, 2
	v_readlane_b32 s6, v251, 2
	s_ashr_i32 s8, s74, 3
	s_add_i32 s4, s4, s23
	v_readlane_b32 s7, v251, 3
	s_and_b64 s[6:7], s[6:7], exec
	s_cselect_b32 s36, s4, s8
	s_ashr_i32 s6, s36, 4
	s_ashr_i32 s37, s36, 31
	s_ashr_i32 s7, s6, 31
	s_lshl_b64 s[8:9], s[36:37], 18
	s_add_u32 s14, s44, s8
	s_addc_u32 s15, s45, s9
	s_lshl_b64 s[10:11], s[6:7], 17
	s_add_u32 s18, s51, s10
	s_addc_u32 s19, s71, s11
	s_add_u32 s24, s2, s8
	s_addc_u32 s25, s3, s9
	s_ashr_i32 s38, s0, 7
	s_lshl_b32 s0, s38, 11
	s_lshl_b32 s12, s16, 11
	s_add_i32 s29, s0, 0
	s_and_b32 s0, s16, 1
	s_add_i32 s28, s12, 0
	s_lshl_b32 s12, s0, 10
	s_add_i32 s29, s29, s12
	s_lshl_b32 s12, s16, 10
	s_sub_i32 s37, s28, s12
	v_and_b32_e32 v0, 63, v4
	s_cmp_le_i32 s74, s13
	v_lshlrev_b32_e32 v102, 3, v0
	s_cbranch_scc0 .LBB0_522
	s_ashr_i32 s17, s16, 31
	s_lshl_b64 s[12:13], s[16:17], 15
	s_add_u32 s40, s14, s12
	s_addc_u32 s41, s15, s13
	s_ashr_i32 s39, s38, 31
	s_lshl_b64 s[12:13], s[38:39], 11
	s_lshl_b32 s30, s0, 6
	s_or_b32 s12, s12, s30
	v_or_b32_e32 v186, s12, v0
	s_lshl_b32 s12, s16, 4
	v_mov_b32_e32 v187, s13
	s_ashr_i32 s13, s12, 31
	s_lshl_b64 s[54:55], s[12:13], 6
	s_add_u32 s54, s24, s54
	v_lshlrev_b32_e32 v6, 4, v0
	v_mov_b32_e32 v7, v1
	s_addc_u32 s55, s25, s55
	s_add_i32 s13, s28, s75
	s_waitcnt vmcnt(0)
	v_lshl_add_u64 v[8:9], s[40:41], 0, v[6:7]
	s_mov_b32 m0, s13
	v_lshlrev_b64 v[2:3], 4, v[186:187]
	global_load_lds_dwordx4 v6, s[40:41]
	v_lshl_add_u64 v[14:15], v[8:9], 0, s[26:27]
	s_add_i32 m0, s13, 0x400
	s_add_i32 s13, s29, s75
	v_lshl_add_u64 v[10:11], s[18:19], 0, v[2:3]
	global_load_lds_dwordx4 v[14:15], off
	s_add_i32 m0, s13, 0x4000
	s_add_i32 s13, s37, s75
	global_load_lds_dwordx4 v[10:11], off
	s_add_i32 m0, s13, 0x6000
	v_lshl_add_u64 v[12:13], s[54:55], 0, v[6:7]
	global_load_lds_dwordx4 v6, s[54:55]
	s_add_i32 m0, s13, 0x8000
	s_add_i32 s13, s75, 0xa000
	s_cmp_lt_i32 s75, 0x14000
	v_lshl_add_u64 v[6:7], v[12:13], 0, s[48:49]
	s_cselect_b32 s13, s13, 0
	s_mov_b64 s[30:31], 0x800
	global_load_lds_dwordx4 v[6:7], off
	v_lshl_add_u64 v[6:7], v[8:9], 0, s[30:31]
	v_lshl_add_u64 v[10:11], v[10:11], 0, s[30:31]
	s_mov_b64 s[40:41], 0x2000
	s_add_i32 s30, s28, s13
	v_lshl_add_u64 v[14:15], v[12:13], 0, s[40:41]
	s_mov_b32 m0, s30
	s_mov_b64 s[40:41], 0xc00
	global_load_lds_dwordx4 v[6:7], off
	v_lshl_add_u64 v[6:7], v[8:9], 0, s[40:41]
	s_add_i32 m0, s30, 0x400
	s_add_i32 s30, s29, s13
	global_load_lds_dwordx4 v[6:7], off
	s_add_i32 m0, s30, 0x4000
	s_add_i32 s13, s37, s13
	global_load_lds_dwordx4 v[10:11], off
	s_add_i32 m0, s13, 0x6000
	s_mov_b64 s[40:41], 0x22000
	global_load_lds_dwordx4 v[14:15], off
	v_lshl_add_u64 v[6:7], v[12:13], 0, s[40:41]
	s_add_i32 m0, s13, 0x8000
	v_mov_b32_e32 v103, v1
	global_load_lds_dwordx4 v[6:7], off
	v_readfirstlane_b32 s13, v193
	s_nop 3
	s_lshr_b32 s13, s13, 8
	s_cmp_eq_u32 s13, 0
	s_cbranch_scc1 .Lmla_nox
	s_waitcnt vmcnt(5)
	s_barrier

.LBB0_526:
	s_barrier
	ds_read_b64_tr_b16 v[82:83], v105 offset:28672
	ds_read_b64_tr_b16 v[84:85], v105 offset:29184
	ds_read_b64_tr_b16 v[86:87], v105 offset:29696
	ds_read_b64_tr_b16 v[88:89], v105 offset:30208
	ds_read_b64_tr_b16 v[90:91], v105 offset:30720
	ds_read_b64_tr_b16 v[92:93], v105 offset:31232
	ds_read_b64_tr_b16 v[94:95], v105 offset:31744
	ds_read_b64_tr_b16 v[96:97], v105 offset:32256
	s_add_i32 s74, s74, 1
	v_readlane_b32 s14, v251, 2
	s_ashr_i32 s0, s74, 3
	s_add_i32 s4, s4, 4
	v_readlane_b32 s15, v251, 3
	s_and_b64 s[14:15], s[14:15], exec
	s_cselect_b32 s14, s4, s0
	s_ashr_i32 s16, s14, 4
	s_ashr_i32 s15, s14, 31
	s_ashr_i32 s17, s16, 31
	s_lshl_b64 s[14:15], s[14:15], 18
	s_lshl_b64 s[16:17], s[16:17], 17
	s_cmp_ge_i32 s74, s1
	v_ashrrev_i32_e32 v189, 31, v188
	v_lshlrev_b32_e32 v230, 3, v104
	s_mov_b32 s13, 1
	s_cselect_b64 s[18:19], -1, 0
	v_exp_f32_e32 v99, v50
	v_exp_f32_e32 v98, v66
	v_exp_f32_e32 v101, v51
	v_exp_f32_e32 v100, v67
	v_exp_f32_e32 v67, v52
	v_exp_f32_e32 v66, v68
	v_exp_f32_e32 v131, v53
	v_exp_f32_e32 v130, v69
	v_pk_add_f32 v[50:51], v[98:99], 0 op_sel_hi:[1,0]
	v_exp_f32_e32 v69, v54
	v_exp_f32_e32 v68, v70
	v_pk_add_f32 v[50:51], v[100:101], v[50:51]
	v_exp_f32_e32 v133, v55
	v_exp_f32_e32 v132, v71
	v_pk_add_f32 v[50:51], v[66:67], v[50:51]
	v_exp_f32_e32 v71, v56
	v_exp_f32_e32 v70, v72
	v_pk_add_f32 v[50:51], v[130:131], v[50:51]
	v_exp_f32_e32 v135, v57
	v_exp_f32_e32 v134, v73
	v_exp_f32_e32 v73, v58
	v_exp_f32_e32 v72, v74
	v_pk_add_f32 v[50:51], v[68:69], v[50:51]
	v_exp_f32_e32 v137, v59
	v_exp_f32_e32 v136, v75
	v_pk_add_f32 v[50:51], v[132:133], v[50:51]
	v_exp_f32_e32 v75, v60
	v_exp_f32_e32 v74, v76
	v_pk_add_f32 v[50:51], v[70:71], v[50:51]
	v_exp_f32_e32 v139, v61
	v_exp_f32_e32 v138, v77
	v_pk_add_f32 v[50:51], v[134:135], v[50:51]
	v_exp_f32_e32 v77, v62
	v_exp_f32_e32 v76, v78
	v_pk_add_f32 v[50:51], v[72:73], v[50:51]
	v_exp_f32_e32 v141, v63
	v_exp_f32_e32 v140, v79
	v_pk_add_f32 v[50:51], v[136:137], v[50:51]
	v_exp_f32_e32 v79, v64
	v_exp_f32_e32 v78, v80
	v_pk_add_f32 v[50:51], v[74:75], v[50:51]
	v_exp_f32_e32 v143, v65
	v_exp_f32_e32 v142, v81
	v_pk_add_f32 v[50:51], v[138:139], v[50:51]
	v_cvt_pk_bf16_f32 v52, v69, v133
	v_pk_add_f32 v[50:51], v[76:77], v[50:51]
	v_cvt_pk_bf16_f32 v53, v71, v135
	v_pk_add_f32 v[50:51], v[140:141], v[50:51]
	v_cvt_pk_bf16_f32 v54, v73, v137
	v_pk_add_f32 v[50:51], v[78:79], v[50:51]
	v_cvt_pk_bf16_f32 v55, v75, v139
	v_pk_add_f32 v[144:145], v[142:143], v[50:51]
	v_cvt_pk_bf16_f32 v51, v67, v131
	v_cvt_pk_bf16_f32 v56, v77, v141
	v_cvt_pk_bf16_f32 v57, v79, v143
	v_cvt_pk_bf16_f32 v59, v66, v130
	v_cvt_pk_bf16_f32 v60, v68, v132
	v_cvt_pk_bf16_f32 v61, v70, v134
	v_cvt_pk_bf16_f32 v62, v72, v136
	v_cvt_pk_bf16_f32 v63, v74, v138
	v_cvt_pk_bf16_f32 v64, v76, v140
	v_cvt_pk_bf16_f32 v65, v78, v142
	ds_read_b64_tr_b16 v[66:67], v105 offset:36864
	ds_read_b64_tr_b16 v[68:69], v105 offset:37376
	ds_read_b64_tr_b16 v[70:71], v105 offset:37888
	ds_read_b64_tr_b16 v[72:73], v105 offset:38400
	ds_read_b64_tr_b16 v[74:75], v105 offset:38912
	ds_read_b64_tr_b16 v[76:77], v105 offset:39424
	ds_read_b64_tr_b16 v[78:79], v105 offset:39936
	ds_read_b64_tr_b16 v[80:81], v105 offset:40448
	v_cvt_pk_bf16_f32 v50, v99, v101
	v_cvt_pk_bf16_f32 v58, v98, v100
	s_waitcnt lgkmcnt(14)
	v_mfma_f32_32x32x16_bf16 v[2:17], v[82:85], v[50:53], v[2:17]
	s_add_i32 s0, s75, 0xa000
	s_cmp_lt_i32 s75, 0x14000
	s_cselect_b32 s75, s0, 0
	v_lshl_add_u64 v[216:217], v[102:103], 1, s[2:3]
	s_movk_i32 s38, 0x80
	s_waitcnt lgkmcnt(6)
	v_mfma_f32_32x32x16_bf16 v[18:33], v[66:69], v[50:53], v[18:33]
	v_add_f32_e32 v50, v144, v145
	v_add_f32_e32 v231, v214, v50
	v_mfma_f32_32x32x16_bf16 v[2:17], v[86:89], v[54:57], v[2:17]
	s_waitcnt lgkmcnt(4)
	v_mfma_f32_32x32x16_bf16 v[18:33], v[70:73], v[54:57], v[18:33]
	v_mfma_f32_32x32x16_bf16 v[2:17], v[90:93], v[58:61], v[2:17]
	s_waitcnt lgkmcnt(2)
	v_mfma_f32_32x32x16_bf16 v[18:33], v[74:77], v[58:61], v[18:33]
	v_mfma_f32_32x32x16_bf16 v[2:17], v[94:97], v[62:65], v[2:17]
	s_waitcnt lgkmcnt(0)
	v_mfma_f32_32x32x16_bf16 v[18:33], v[78:81], v[62:65], v[18:33]
	s_branch .LBB0_528
.LBB0_527:
	s_waitcnt vmcnt(0)
	s_barrier
	s_cmp_gt_u32 s13, 13
	s_cselect_b64 s[24:25], -1, 0
	s_and_b64 s[40:41], s[24:25], s[18:19]
	s_and_b64 vcc, exec, s[40:41]
	s_cbranch_vccnz .Lmla_nodma
	s_and_b64 s[24:25], s[24:25], exec
	s_movk_i32 s30, 0xf900
	s_cselect_b32 s25, s15, s9
	s_cselect_b32 s24, s14, s8
	s_cselect_b32 s0, s17, s11
	s_cselect_b32 s4, s16, s10
	s_cselect_b32 s30, s30, 0x100
	s_cmp_gt_i32 s75, 0x9fff
	s_cselect_b32 s31, s68, 0x14000
	s_add_i32 s31, s31, s75
	s_add_u32 s40, s51, s4
	s_addc_u32 s41, s71, s0
	s_add_u32 s54, s44, s24
	s_addc_u32 s55, s45, s25
	s_add_i32 s4, s30, s38
	v_lshl_add_u64 v[154:155], v[190:191], 0, s[4:5]
	s_add_i32 s0, s28, s31
	v_lshl_add_u64 v[152:153], v[216:217], 0, s[24:25]
	v_lshl_add_u64 v[154:155], v[154:155], 4, s[54:55]
	s_add_i32 s24, s4, s12
	s_mov_b32 m0, s0
	v_lshl_add_u64 v[156:157], v[186:187], 0, s[4:5]
	s_ashr_i32 s25, s24, 31
	global_load_lds_dwordx4 v[154:155], off
	v_lshl_add_u64 v[154:155], v[154:155], 0, s[26:27]
	s_add_i32 m0, s0, 0x400
	s_add_i32 s0, s29, s31
	v_lshl_add_u64 v[156:157], v[156:157], 4, s[40:41]
	s_lshl_b64 s[24:25], s[24:25], 6
	global_load_lds_dwordx4 v[154:155], off
	s_add_i32 m0, s0, 0x4000
	s_add_i32 s0, s37, s31
	v_lshl_add_u64 v[152:153], v[152:153], 0, s[24:25]
	global_load_lds_dwordx4 v[156:157], off
	s_add_i32 m0, s0, 0x6000
	s_nop 0
	global_load_lds_dwordx4 v[152:153], off
	v_lshl_add_u64 v[152:153], v[152:153], 0, s[48:49]
	s_add_i32 m0, s0, 0x8000
	s_nop 0
	global_load_lds_dwordx4 v[152:153], off

.Lmla_exit:
	v_readfirstlane_b32 s0, v193
	s_nop 3
	s_lshr_b32 s0, s0, 8
	s_cmp_lg_u32 s0, 0
	s_cbranch_scc1 .LBB0_538
	s_barrier
